# v30 + SB attention QK^T: the 16 K-fragment ds_read_b128 per tile rotate through 8 register quads with 6 reads in flight and counted lgkmcnt waits (was one quad, lgkmcnt(0) before every MFMA)
# speedup vs baseline: 1.0017x; 1.0017x over previous
.LBB0_667:
	s_lshl_b32 s53, s21, 14
	v_add_u32_e32 v34, s53, v191
	v_add_u32_e32 v40, v34, v192
	ds_read_b128 v[224:227], v40 offset:32768
	ds_read_b128 v[228:231], v40 offset:40960
	v_add_u32_e32 v40, v34, v193
	ds_read_b128 v[232:235], v40 offset:32768
	ds_read_b128 v[236:239], v40 offset:40960
	v_add_u32_e32 v40, v34, v194
	ds_read_b128 v[240:243], v40 offset:32768
	ds_read_b128 v[244:247], v40 offset:40960
	v_add_u32_e32 v40, v34, v195
	s_mov_b32 s4, 0x3e0293ee
	s_cmp_ge_i32 s34, s9
	s_cselect_b64 s[48:49], -1, 0
	s_cmp_lt_i32 s34, s9
	v_cmp_lt_i32_e64 s[46:47], 0, v201
	v_cmp_lt_i32_e64 s[44:45], 1, v201
	v_cmp_lt_i32_e64 s[42:43], 32, v201
	v_cmp_lt_i32_e32 vcc, 33, v201
	s_waitcnt vmcnt(7) lgkmcnt(5)
	v_mfma_f32_32x32x16_bf16 v[82:97], v[224:227], v[122:125], 0
	ds_read_b128 v[248:251], v40 offset:32768
	s_waitcnt lgkmcnt(5)
	v_mfma_f32_32x32x16_bf16 v[98:113], v[228:231], v[122:125], 0
	ds_read_b128 v[36:39], v40 offset:40960
	v_add_u32_e32 v40, v34, v196
	s_waitcnt vmcnt(6) lgkmcnt(5)
	v_mfma_f32_32x32x16_bf16 v[82:97], v[232:235], v[126:129], v[82:97]
	ds_read_b128 v[224:227], v40 offset:32768
	s_waitcnt lgkmcnt(5)
	v_mfma_f32_32x32x16_bf16 v[98:113], v[236:239], v[126:129], v[98:113]
	ds_read_b128 v[228:231], v40 offset:40960
	v_add_u32_e32 v40, v34, v197
	s_waitcnt vmcnt(5) lgkmcnt(5)
	v_mfma_f32_32x32x16_bf16 v[82:97], v[240:243], v[130:133], v[82:97]
	ds_read_b128 v[232:235], v40 offset:32768
	s_waitcnt lgkmcnt(5)
	v_mfma_f32_32x32x16_bf16 v[98:113], v[244:247], v[130:133], v[98:113]
	ds_read_b128 v[236:239], v40 offset:40960
	v_add_u32_e32 v40, v34, v198
	s_waitcnt vmcnt(4) lgkmcnt(5)
	v_mfma_f32_32x32x16_bf16 v[82:97], v[248:251], v[134:137], v[82:97]
	ds_read_b128 v[240:243], v40 offset:32768
	s_waitcnt lgkmcnt(5)
	v_mfma_f32_32x32x16_bf16 v[98:113], v[36:39], v[134:137], v[98:113]
	ds_read_b128 v[244:247], v40 offset:40960
	v_add_u32_e32 v40, v34, v199
	s_waitcnt vmcnt(3) lgkmcnt(5)
	v_mfma_f32_32x32x16_bf16 v[82:97], v[224:227], v[138:141], v[82:97]
	ds_read_b128 v[248:251], v40 offset:32768
	s_waitcnt lgkmcnt(5)
	v_mfma_f32_32x32x16_bf16 v[98:113], v[228:231], v[138:141], v[98:113]
	ds_read_b128 v[36:39], v40 offset:40960
	s_waitcnt vmcnt(2) lgkmcnt(5)
	v_mfma_f32_32x32x16_bf16 v[82:97], v[232:235], v[142:145], v[82:97]
	s_waitcnt lgkmcnt(4)
	v_mfma_f32_32x32x16_bf16 v[98:113], v[236:239], v[142:145], v[98:113]
	s_waitcnt vmcnt(1) lgkmcnt(3)
	v_mfma_f32_32x32x16_bf16 v[82:97], v[240:243], v[146:149], v[82:97]
	s_waitcnt lgkmcnt(2)
	v_mfma_f32_32x32x16_bf16 v[98:113], v[244:247], v[146:149], v[98:113]
	s_waitcnt vmcnt(0) lgkmcnt(1)
	v_mfma_f32_32x32x16_bf16 v[82:97], v[248:251], v[154:157], v[82:97]
	s_waitcnt lgkmcnt(0)
	v_mfma_f32_32x32x16_bf16 v[98:113], v[36:39], v[154:157], v[98:113]
	s_nop 10
	v_mul_f32_e64 v38, v82, s4
	v_mul_f32_e64 v39, v83, s4
	v_exp_f32_e64 v40, -|v38|
	v_exp_f32_e64 v41, -|v39|
	v_max_f32_e32 v44, 0, v38
	v_max_f32_e32 v45, 0, v39
	v_pk_mul_f32 v[36:37], v[98:99], s[4:5] op_sel_hi:[1,0]
	s_nop 0
	v_exp_f32_e64 v42, -|v36|
	v_exp_f32_e64 v43, -|v37|
	v_pk_add_f32 v[40:41], v[40:41], 1.0 op_sel_hi:[1,0]
	v_pk_add_f32 v[42:43], v[42:43], 1.0 op_sel_hi:[1,0]
	v_log_f32_e32 v40, v40
	v_log_f32_e32 v41, v41
	v_log_f32_e32 v42, v42
	v_log_f32_e32 v43, v43
	v_pk_add_f32 v[44:45], v[44:45], v[40:41]
	v_max_f32_e32 v40, 0, v36
	v_max_f32_e32 v41, 0, v37
	v_pk_add_f32 v[82:83], v[40:41], v[42:43]
	s_cbranch_scc0 .Lsbd_668
